# gated projection epilogue (E_PROJA/E_PROJB): gate and merged rows fetched four steps at a time with counted vmcnt and plain f32 VALU, same arithmetic order
# speedup vs baseline: 1.0134x; 1.0100x over previous
; DI float bf_lo(unsigned u) { return __uint_as_float(u << 16); }
; DI float bf_hi(unsigned u) { return __uint_as_float(u & 0xffff0000u); }
; #define EPI_ROWS for (int ai = 0; ai < 2; ++ai) for (int m = 0; m < 4; ++m, ({ asm volatile("" ::: "memory"); }))
; DI void store_bf8(bf16_t* p, f32x4 a, f32x4 b) { u32x4 w; w.x = pk2(a[0], a[1]); w.y = pk2(a[2], a[3]); w.z = pk2(b[0], b[1]); w.w = pk2(b[2], b[3]); *(u32x4*)p = w; }
; DI void gemm_run(const GemmDesc& d, char* lds) {
;     ...
;         case E_PROJA: case E_PROJB: {
;             const int goff = d.epi == E_PROJA ? 0 : 1024, c8 = bcol + wc * 32 + fq * 8;
; #pragma unroll
;             EPI_ROWS { const int row = rbase + ai * 128 + m * 16;
; #pragma unroll
;                 for (int bj = 0; bj < 2; ++bj) { const int c = c8 + bj * 128; const u32x4 gw = *(const u32x4*)(P->gates + (long)row * 2048 + goff + c);
;                     f32x4 g0 = {bf_lo(gw.x), bf_hi(gw.x), bf_lo(gw.y), bf_hi(gw.y)}, g1 = {bf_lo(gw.z), bf_hi(gw.z), bf_lo(gw.w), bf_hi(gw.w)};
;                     f32x4 v0 = acc[ai][bj][m][0] * g0, v1 = acc[ai][bj][m][1] * g1;
;                     bf16_t* dst = P->merged + (long)row * 1024 + c;
;                     if (d.epi == E_PROJB) { const u32x4 pw = *(const u32x4*)dst;
;                         v0 += (f32x4){bf_lo(pw.x), bf_hi(pw.x), bf_lo(pw.y), bf_hi(pw.y)}; v1 += (f32x4){bf_lo(pw.z), bf_hi(pw.z), bf_lo(pw.w), bf_hi(pw.w)}; }
;                     store_bf8(dst, v0, v1); } }
.LBB0_613:
	s_andn2_b64 vcc, exec, s[2:3]
	s_cbranch_vccnz .LBB0_778
	s_cmp_lg_u32 s65, 3
	s_mov_b64 s[2:3], -1
	s_cbranch_scc0 .LBB0_648
	s_load_dwordx4 s[8:11], s[58:59], 0x168
	v_lshl_add_u32 v128, v206, 3, s63
	v_lshlrev_b32_e32 v128, 1, v128
	v_lshl_add_u32 v130, v146, 12, v128
	v_lshl_add_u32 v131, v146, 11, v128
	s_waitcnt lgkmcnt(0)
	s_add_u32 s2, s8, s20
	s_addc_u32 s3, s9, 0
	s_andn2_b64 vcc, exec, s[52:53]
	s_cbranch_vccnz .Lproj_a
	v_mov_b32_e32 v128, v130
	global_load_dwordx4 v[208:211], v128, s[2:3]
	v_mov_b32_e32 v129, v131
	global_load_dwordx4 v[224:227], v129, s[10:11]
	v_mov_b32_e32 v128, v130
	global_load_dwordx4 v[212:215], v128, s[2:3] offset:256
	v_mov_b32_e32 v129, v131
	global_load_dwordx4 v[228:231], v129, s[10:11] offset:256
	v_add_u32_e32 v128, 0x10000, v130
	global_load_dwordx4 v[216:219], v128, s[2:3]
	v_add_u32_e32 v129, 0x8000, v131
	global_load_dwordx4 v[232:235], v129, s[10:11]
	v_add_u32_e32 v128, 0x10000, v130
	global_load_dwordx4 v[220:223], v128, s[2:3] offset:256
	v_add_u32_e32 v129, 0x8000, v131
	global_load_dwordx4 v[236:239], v129, s[10:11] offset:256
	s_waitcnt vmcnt(6)
	v_lshlrev_b32_e32 v240, 16, v208
	v_and_b32_e32 v241, 0xffff0000, v208
	v_lshlrev_b32_e32 v242, 16, v209
	v_and_b32_e32 v243, 0xffff0000, v209
	v_lshlrev_b32_e32 v244, 16, v210
	v_and_b32_e32 v245, 0xffff0000, v210
	v_lshlrev_b32_e32 v246, 16, v211
	v_and_b32_e32 v247, 0xffff0000, v211
	v_mul_f32_e32 v240, v124, v240
	v_mul_f32_e32 v241, v125, v241
	v_mul_f32_e32 v242, v126, v242
	v_mul_f32_e32 v243, v127, v243
	v_mul_f32_e32 v244, v120, v244
	v_mul_f32_e32 v245, v121, v245
	v_mul_f32_e32 v246, v122, v246
	v_mul_f32_e32 v247, v123, v247
	v_lshlrev_b32_e32 v150, 16, v224
	v_and_b32_e32 v151, 0xffff0000, v224
	v_lshlrev_b32_e32 v152, 16, v225
	v_and_b32_e32 v153, 0xffff0000, v225
	v_lshlrev_b32_e32 v154, 16, v226
	v_and_b32_e32 v155, 0xffff0000, v226
	v_lshlrev_b32_e32 v156, 16, v227
	v_and_b32_e32 v157, 0xffff0000, v227
	v_add_f32_e32 v240, v240, v150
	v_add_f32_e32 v241, v241, v151
	v_add_f32_e32 v242, v242, v152
	v_add_f32_e32 v243, v243, v153
	v_add_f32_e32 v244, v244, v154
	v_add_f32_e32 v245, v245, v155
	v_add_f32_e32 v246, v246, v156
	v_add_f32_e32 v247, v247, v157
	v_cvt_pk_bf16_f32 v158, v240, v241
	v_cvt_pk_bf16_f32 v159, v242, v243
	v_cvt_pk_bf16_f32 v160, v244, v245
	v_cvt_pk_bf16_f32 v161, v246, v247
	v_mov_b32_e32 v129, v131
	global_store_dwordx4 v129, v[158:161], s[10:11]
	s_waitcnt vmcnt(5)
	v_lshlrev_b32_e32 v240, 16, v212
	v_and_b32_e32 v241, 0xffff0000, v212
	v_lshlrev_b32_e32 v242, 16, v213
	v_and_b32_e32 v243, 0xffff0000, v213
	v_lshlrev_b32_e32 v244, 16, v214
	v_and_b32_e32 v245, 0xffff0000, v214
	v_lshlrev_b32_e32 v246, 16, v215
	v_and_b32_e32 v247, 0xffff0000, v215
	v_mul_f32_e32 v240, v108, v240
	v_mul_f32_e32 v241, v109, v241
	v_mul_f32_e32 v242, v110, v242
	v_mul_f32_e32 v243, v111, v243
	v_mul_f32_e32 v244, v104, v244
	v_mul_f32_e32 v245, v105, v245
	v_mul_f32_e32 v246, v106, v246
	v_mul_f32_e32 v247, v107, v247
	v_lshlrev_b32_e32 v150, 16, v228
	v_and_b32_e32 v151, 0xffff0000, v228
	v_lshlrev_b32_e32 v152, 16, v229
	v_and_b32_e32 v153, 0xffff0000, v229
	v_lshlrev_b32_e32 v154, 16, v230
	v_and_b32_e32 v155, 0xffff0000, v230
	v_lshlrev_b32_e32 v156, 16, v231
	v_and_b32_e32 v157, 0xffff0000, v231
	v_add_f32_e32 v240, v240, v150
	v_add_f32_e32 v241, v241, v151
	v_add_f32_e32 v242, v242, v152
	v_add_f32_e32 v243, v243, v153
	v_add_f32_e32 v244, v244, v154
	v_add_f32_e32 v245, v245, v155
	v_add_f32_e32 v246, v246, v156
	v_add_f32_e32 v247, v247, v157
	v_cvt_pk_bf16_f32 v166, v240, v241
	v_cvt_pk_bf16_f32 v167, v242, v243
	v_cvt_pk_bf16_f32 v168, v244, v245
	v_cvt_pk_bf16_f32 v169, v246, v247
	v_mov_b32_e32 v129, v131
	global_store_dwordx4 v129, v[166:169], s[10:11] offset:256
	s_waitcnt vmcnt(4)
	v_lshlrev_b32_e32 v240, 16, v216
	v_and_b32_e32 v241, 0xffff0000, v216
	v_lshlrev_b32_e32 v242, 16, v217
	v_and_b32_e32 v243, 0xffff0000, v217
	v_lshlrev_b32_e32 v244, 16, v218
	v_and_b32_e32 v245, 0xffff0000, v218
	v_lshlrev_b32_e32 v246, 16, v219
	v_and_b32_e32 v247, 0xffff0000, v219
	v_mul_f32_e32 v240, v116, v240
	v_mul_f32_e32 v241, v117, v241
	v_mul_f32_e32 v242, v118, v242
	v_mul_f32_e32 v243, v119, v243
	v_mul_f32_e32 v244, v112, v244
	v_mul_f32_e32 v245, v113, v245
	v_mul_f32_e32 v246, v114, v246
	v_mul_f32_e32 v247, v115, v247
	v_lshlrev_b32_e32 v150, 16, v232
	v_and_b32_e32 v151, 0xffff0000, v232
	v_lshlrev_b32_e32 v152, 16, v233
	v_and_b32_e32 v153, 0xffff0000, v233
	v_lshlrev_b32_e32 v154, 16, v234
	v_and_b32_e32 v155, 0xffff0000, v234
	v_lshlrev_b32_e32 v156, 16, v235
	v_and_b32_e32 v157, 0xffff0000, v235
	v_add_f32_e32 v240, v240, v150
	v_add_f32_e32 v241, v241, v151
	v_add_f32_e32 v242, v242, v152
	v_add_f32_e32 v243, v243, v153
	v_add_f32_e32 v244, v244, v154
	v_add_f32_e32 v245, v245, v155
	v_add_f32_e32 v246, v246, v156
	v_add_f32_e32 v247, v247, v157
	v_cvt_pk_bf16_f32 v158, v240, v241
	v_cvt_pk_bf16_f32 v159, v242, v243
	v_cvt_pk_bf16_f32 v160, v244, v245
	v_cvt_pk_bf16_f32 v161, v246, v247
	v_add_u32_e32 v129, 0x8000, v131
	global_store_dwordx4 v129, v[158:161], s[10:11]
	s_waitcnt vmcnt(3)
; DI float bf_lo(unsigned u) { return __uint_as_float(u << 16); }
; DI float bf_hi(unsigned u) { return __uint_as_float(u & 0xffff0000u); }
; #define EPI_ROWS for (int ai = 0; ai < 2; ++ai) for (int m = 0; m < 4; ++m, ({ asm volatile("" ::: "memory"); }))
; DI void store_bf8(bf16_t* p, f32x4 a, f32x4 b) { u32x4 w; w.x = pk2(a[0], a[1]); w.y = pk2(a[2], a[3]); w.z = pk2(b[0], b[1]); w.w = pk2(b[2], b[3]); *(u32x4*)p = w; }
; DI void gemm_run(const GemmDesc& d, char* lds) {
;     ...
;         case E_PROJA: case E_PROJB: {
;             const int goff = d.epi == E_PROJA ? 0 : 1024, c8 = bcol + wc * 32 + fq * 8;
; #pragma unroll
;             EPI_ROWS { const int row = rbase + ai * 128 + m * 16;
; #pragma unroll
;                 for (int bj = 0; bj < 2; ++bj) { const int c = c8 + bj * 128; const u32x4 gw = *(const u32x4*)(P->gates + (long)row * 2048 + goff + c);
;                     f32x4 g0 = {bf_lo(gw.x), bf_hi(gw.x), bf_lo(gw.y), bf_hi(gw.y)}, g1 = {bf_lo(gw.z), bf_hi(gw.z), bf_lo(gw.w), bf_hi(gw.w)};
;                     f32x4 v0 = acc[ai][bj][m][0] * g0, v1 = acc[ai][bj][m][1] * g1;
;                     bf16_t* dst = P->merged + (long)row * 1024 + c;
;                     if (d.epi == E_PROJB) { const u32x4 pw = *(const u32x4*)dst;
;                         v0 += (f32x4){bf_lo(pw.x), bf_hi(pw.x), bf_lo(pw.y), bf_hi(pw.y)}; v1 += (f32x4){bf_lo(pw.z), bf_hi(pw.z), bf_lo(pw.w), bf_hi(pw.w)}; }
;                     store_bf8(dst, v0, v1); } }
	v_lshlrev_b32_e32 v240, 16, v220
	v_and_b32_e32 v241, 0xffff0000, v220
	v_lshlrev_b32_e32 v242, 16, v221
	v_and_b32_e32 v243, 0xffff0000, v221
	v_lshlrev_b32_e32 v244, 16, v222
	v_and_b32_e32 v245, 0xffff0000, v222
	v_lshlrev_b32_e32 v246, 16, v223
	v_and_b32_e32 v247, 0xffff0000, v223
	v_mul_f32_e32 v240, v92, v240
	v_mul_f32_e32 v241, v93, v241
	v_mul_f32_e32 v242, v94, v242
	v_mul_f32_e32 v243, v95, v243
	v_mul_f32_e32 v244, v88, v244
	v_mul_f32_e32 v245, v89, v245
	v_mul_f32_e32 v246, v90, v246
	v_mul_f32_e32 v247, v91, v247
	v_lshlrev_b32_e32 v150, 16, v236
	v_and_b32_e32 v151, 0xffff0000, v236
	v_lshlrev_b32_e32 v152, 16, v237
	v_and_b32_e32 v153, 0xffff0000, v237
	v_lshlrev_b32_e32 v154, 16, v238
	v_and_b32_e32 v155, 0xffff0000, v238
	v_lshlrev_b32_e32 v156, 16, v239
	v_and_b32_e32 v157, 0xffff0000, v239
	v_add_f32_e32 v240, v240, v150
	v_add_f32_e32 v241, v241, v151
	v_add_f32_e32 v242, v242, v152
	v_add_f32_e32 v243, v243, v153
	v_add_f32_e32 v244, v244, v154
	v_add_f32_e32 v245, v245, v155
	v_add_f32_e32 v246, v246, v156
	v_add_f32_e32 v247, v247, v157
	v_cvt_pk_bf16_f32 v166, v240, v241
	v_cvt_pk_bf16_f32 v167, v242, v243
	v_cvt_pk_bf16_f32 v168, v244, v245
	v_cvt_pk_bf16_f32 v169, v246, v247
	v_add_u32_e32 v129, 0x8000, v131
	global_store_dwordx4 v129, v[166:169], s[10:11] offset:256
	v_add_u32_e32 v128, 0x20000, v130
	global_load_dwordx4 v[208:211], v128, s[2:3]
	v_add_u32_e32 v129, 0x10000, v131
	global_load_dwordx4 v[224:227], v129, s[10:11]
	v_add_u32_e32 v128, 0x20000, v130
	global_load_dwordx4 v[212:215], v128, s[2:3] offset:256
	v_add_u32_e32 v129, 0x10000, v131
	global_load_dwordx4 v[228:231], v129, s[10:11] offset:256
	v_add_u32_e32 v128, 0x30000, v130
	global_load_dwordx4 v[216:219], v128, s[2:3]
	v_add_u32_e32 v129, 0x18000, v131
	global_load_dwordx4 v[232:235], v129, s[10:11]
	v_add_u32_e32 v128, 0x30000, v130
	global_load_dwordx4 v[220:223], v128, s[2:3] offset:256
	v_add_u32_e32 v129, 0x18000, v131
	global_load_dwordx4 v[236:239], v129, s[10:11] offset:256
	s_waitcnt vmcnt(6)
	v_lshlrev_b32_e32 v240, 16, v208
	v_and_b32_e32 v241, 0xffff0000, v208
	v_lshlrev_b32_e32 v242, 16, v209
	v_and_b32_e32 v243, 0xffff0000, v209
	v_lshlrev_b32_e32 v244, 16, v210
	v_and_b32_e32 v245, 0xffff0000, v210
	v_lshlrev_b32_e32 v246, 16, v211
	v_and_b32_e32 v247, 0xffff0000, v211
	v_mul_f32_e32 v240, v100, v240
	v_mul_f32_e32 v241, v101, v241
	v_mul_f32_e32 v242, v102, v242
	v_mul_f32_e32 v243, v103, v243
	v_mul_f32_e32 v244, v96, v244
	v_mul_f32_e32 v245, v97, v245
	v_mul_f32_e32 v246, v98, v246
	v_mul_f32_e32 v247, v99, v247
	v_lshlrev_b32_e32 v150, 16, v224
	v_and_b32_e32 v151, 0xffff0000, v224
	v_lshlrev_b32_e32 v152, 16, v225
	v_and_b32_e32 v153, 0xffff0000, v225
	v_lshlrev_b32_e32 v154, 16, v226
	v_and_b32_e32 v155, 0xffff0000, v226
	v_lshlrev_b32_e32 v156, 16, v227
	v_and_b32_e32 v157, 0xffff0000, v227
	v_add_f32_e32 v240, v240, v150
	v_add_f32_e32 v241, v241, v151
	v_add_f32_e32 v242, v242, v152
	v_add_f32_e32 v243, v243, v153
	v_add_f32_e32 v244, v244, v154
	v_add_f32_e32 v245, v245, v155
	v_add_f32_e32 v246, v246, v156
	v_add_f32_e32 v247, v247, v157
	v_cvt_pk_bf16_f32 v158, v240, v241
	v_cvt_pk_bf16_f32 v159, v242, v243
	v_cvt_pk_bf16_f32 v160, v244, v245
	v_cvt_pk_bf16_f32 v161, v246, v247
	v_add_u32_e32 v129, 0x10000, v131
	global_store_dwordx4 v129, v[158:161], s[10:11]
	s_waitcnt vmcnt(5)
	v_lshlrev_b32_e32 v240, 16, v212
	v_and_b32_e32 v241, 0xffff0000, v212
	v_lshlrev_b32_e32 v242, 16, v213
	v_and_b32_e32 v243, 0xffff0000, v213
	v_lshlrev_b32_e32 v244, 16, v214
	v_and_b32_e32 v245, 0xffff0000, v214
	v_lshlrev_b32_e32 v246, 16, v215
	v_and_b32_e32 v247, 0xffff0000, v215
	v_mul_f32_e32 v240, v76, v240
	v_mul_f32_e32 v241, v77, v241
	v_mul_f32_e32 v242, v78, v242
	v_mul_f32_e32 v243, v79, v243
	v_mul_f32_e32 v244, v72, v244
	v_mul_f32_e32 v245, v73, v245
	v_mul_f32_e32 v246, v74, v246
	v_mul_f32_e32 v247, v75, v247
	v_lshlrev_b32_e32 v150, 16, v228
	v_and_b32_e32 v151, 0xffff0000, v228
	v_lshlrev_b32_e32 v152, 16, v229
	v_and_b32_e32 v153, 0xffff0000, v229
	v_lshlrev_b32_e32 v154, 16, v230
	v_and_b32_e32 v155, 0xffff0000, v230
	v_lshlrev_b32_e32 v156, 16, v231
	v_and_b32_e32 v157, 0xffff0000, v231
	v_add_f32_e32 v240, v240, v150
	v_add_f32_e32 v241, v241, v151
	v_add_f32_e32 v242, v242, v152
	v_add_f32_e32 v243, v243, v153
	v_add_f32_e32 v244, v244, v154
	v_add_f32_e32 v245, v245, v155
	v_add_f32_e32 v246, v246, v156
	v_add_f32_e32 v247, v247, v157
	v_cvt_pk_bf16_f32 v166, v240, v241
	v_cvt_pk_bf16_f32 v167, v242, v243
	v_cvt_pk_bf16_f32 v168, v244, v245
	v_cvt_pk_bf16_f32 v169, v246, v247
	v_add_u32_e32 v129, 0x10000, v131
	global_store_dwordx4 v129, v[166:169], s[10:11] offset:256
	s_waitcnt vmcnt(4)
	v_lshlrev_b32_e32 v240, 16, v216
	v_and_b32_e32 v241, 0xffff0000, v216
	v_lshlrev_b32_e32 v242, 16, v217
	v_and_b32_e32 v243, 0xffff0000, v217
	v_lshlrev_b32_e32 v244, 16, v218
	v_and_b32_e32 v245, 0xffff0000, v218
	v_lshlrev_b32_e32 v246, 16, v219
	v_and_b32_e32 v247, 0xffff0000, v219
	v_mul_f32_e32 v240, v84, v240
	v_mul_f32_e32 v241, v85, v241
	v_mul_f32_e32 v242, v86, v242
	v_mul_f32_e32 v243, v87, v243
	v_mul_f32_e32 v244, v80, v244
	v_mul_f32_e32 v245, v81, v245
	v_mul_f32_e32 v246, v82, v246
	v_mul_f32_e32 v247, v83, v247
	v_lshlrev_b32_e32 v150, 16, v232
	v_and_b32_e32 v151, 0xffff0000, v232
	v_lshlrev_b32_e32 v152, 16, v233
	v_and_b32_e32 v153, 0xffff0000, v233
	v_lshlrev_b32_e32 v154, 16, v234
	v_and_b32_e32 v155, 0xffff0000, v234
	v_lshlrev_b32_e32 v156, 16, v235
	v_and_b32_e32 v157, 0xffff0000, v235
	v_add_f32_e32 v240, v240, v150
	v_add_f32_e32 v241, v241, v151
	v_add_f32_e32 v242, v242, v152
	v_add_f32_e32 v243, v243, v153
	v_add_f32_e32 v244, v244, v154
	v_add_f32_e32 v245, v245, v155
	v_add_f32_e32 v246, v246, v156
	v_add_f32_e32 v247, v247, v157
	v_cvt_pk_bf16_f32 v158, v240, v241
	v_cvt_pk_bf16_f32 v159, v242, v243
	v_cvt_pk_bf16_f32 v160, v244, v245
	v_cvt_pk_bf16_f32 v161, v246, v247
	v_add_u32_e32 v129, 0x18000, v131
	global_store_dwordx4 v129, v[158:161], s[10:11]
	s_waitcnt vmcnt(3)
; DI float bf_lo(unsigned u) { return __uint_as_float(u << 16); }
; DI float bf_hi(unsigned u) { return __uint_as_float(u & 0xffff0000u); }
; #define EPI_ROWS for (int ai = 0; ai < 2; ++ai) for (int m = 0; m < 4; ++m, ({ asm volatile("" ::: "memory"); }))
; DI void store_bf8(bf16_t* p, f32x4 a, f32x4 b) { u32x4 w; w.x = pk2(a[0], a[1]); w.y = pk2(a[2], a[3]); w.z = pk2(b[0], b[1]); w.w = pk2(b[2], b[3]); *(u32x4*)p = w; }
; DI void gemm_run(const GemmDesc& d, char* lds) {
;     ...
;         case E_PROJA: case E_PROJB: {
;             const int goff = d.epi == E_PROJA ? 0 : 1024, c8 = bcol + wc * 32 + fq * 8;
; #pragma unroll
;             EPI_ROWS { const int row = rbase + ai * 128 + m * 16;
; #pragma unroll
;                 for (int bj = 0; bj < 2; ++bj) { const int c = c8 + bj * 128; const u32x4 gw = *(const u32x4*)(P->gates + (long)row * 2048 + goff + c);
;                     f32x4 g0 = {bf_lo(gw.x), bf_hi(gw.x), bf_lo(gw.y), bf_hi(gw.y)}, g1 = {bf_lo(gw.z), bf_hi(gw.z), bf_lo(gw.w), bf_hi(gw.w)};
;                     f32x4 v0 = acc[ai][bj][m][0] * g0, v1 = acc[ai][bj][m][1] * g1;
;                     bf16_t* dst = P->merged + (long)row * 1024 + c;
;                     if (d.epi == E_PROJB) { const u32x4 pw = *(const u32x4*)dst;
;                         v0 += (f32x4){bf_lo(pw.x), bf_hi(pw.x), bf_lo(pw.y), bf_hi(pw.y)}; v1 += (f32x4){bf_lo(pw.z), bf_hi(pw.z), bf_lo(pw.w), bf_hi(pw.w)}; }
;                     store_bf8(dst, v0, v1); } }
	v_lshlrev_b32_e32 v240, 16, v220
	v_and_b32_e32 v241, 0xffff0000, v220
	v_lshlrev_b32_e32 v242, 16, v221
	v_and_b32_e32 v243, 0xffff0000, v221
	v_lshlrev_b32_e32 v244, 16, v222
	v_and_b32_e32 v245, 0xffff0000, v222
	v_lshlrev_b32_e32 v246, 16, v223
	v_and_b32_e32 v247, 0xffff0000, v223
	v_mul_f32_e32 v240, v68, v240
	v_mul_f32_e32 v241, v69, v241
	v_mul_f32_e32 v242, v70, v242
	v_mul_f32_e32 v243, v71, v243
	v_mul_f32_e32 v244, v64, v244
	v_mul_f32_e32 v245, v65, v245
	v_mul_f32_e32 v246, v66, v246
	v_mul_f32_e32 v247, v67, v247
	v_lshlrev_b32_e32 v150, 16, v236
	v_and_b32_e32 v151, 0xffff0000, v236
	v_lshlrev_b32_e32 v152, 16, v237
	v_and_b32_e32 v153, 0xffff0000, v237
	v_lshlrev_b32_e32 v154, 16, v238
	v_and_b32_e32 v155, 0xffff0000, v238
	v_lshlrev_b32_e32 v156, 16, v239
	v_and_b32_e32 v157, 0xffff0000, v239
	v_add_f32_e32 v240, v240, v150
	v_add_f32_e32 v241, v241, v151
	v_add_f32_e32 v242, v242, v152
	v_add_f32_e32 v243, v243, v153
	v_add_f32_e32 v244, v244, v154
	v_add_f32_e32 v245, v245, v155
	v_add_f32_e32 v246, v246, v156
	v_add_f32_e32 v247, v247, v157
	v_cvt_pk_bf16_f32 v166, v240, v241
	v_cvt_pk_bf16_f32 v167, v242, v243
	v_cvt_pk_bf16_f32 v168, v244, v245
	v_cvt_pk_bf16_f32 v169, v246, v247
	v_add_u32_e32 v129, 0x18000, v131
	global_store_dwordx4 v129, v[166:169], s[10:11] offset:256
	v_add_u32_e32 v128, 0x80000, v130
	global_load_dwordx4 v[208:211], v128, s[2:3]
	v_add_u32_e32 v129, 0x40000, v131
	global_load_dwordx4 v[224:227], v129, s[10:11]
	v_add_u32_e32 v128, 0x80000, v130
	global_load_dwordx4 v[212:215], v128, s[2:3] offset:256
	v_add_u32_e32 v129, 0x40000, v131
	global_load_dwordx4 v[228:231], v129, s[10:11] offset:256
	v_add_u32_e32 v128, 0x90000, v130
	global_load_dwordx4 v[216:219], v128, s[2:3]
	v_add_u32_e32 v129, 0x48000, v131
	global_load_dwordx4 v[232:235], v129, s[10:11]
	v_add_u32_e32 v128, 0x90000, v130
	global_load_dwordx4 v[220:223], v128, s[2:3] offset:256
	v_add_u32_e32 v129, 0x48000, v131
	global_load_dwordx4 v[236:239], v129, s[10:11] offset:256
	s_waitcnt vmcnt(6)
	v_lshlrev_b32_e32 v240, 16, v208
	v_and_b32_e32 v241, 0xffff0000, v208
	v_lshlrev_b32_e32 v242, 16, v209
	v_and_b32_e32 v243, 0xffff0000, v209
	v_lshlrev_b32_e32 v244, 16, v210
	v_and_b32_e32 v245, 0xffff0000, v210
	v_lshlrev_b32_e32 v246, 16, v211
	v_and_b32_e32 v247, 0xffff0000, v211
	v_mul_f32_e32 v240, v60, v240
	v_mul_f32_e32 v241, v61, v241
	v_mul_f32_e32 v242, v62, v242
	v_mul_f32_e32 v243, v63, v243
	v_mul_f32_e32 v244, v56, v244
	v_mul_f32_e32 v245, v57, v245
	v_mul_f32_e32 v246, v58, v246
	v_mul_f32_e32 v247, v59, v247
	v_lshlrev_b32_e32 v150, 16, v224
	v_and_b32_e32 v151, 0xffff0000, v224
	v_lshlrev_b32_e32 v152, 16, v225
	v_and_b32_e32 v153, 0xffff0000, v225
	v_lshlrev_b32_e32 v154, 16, v226
	v_and_b32_e32 v155, 0xffff0000, v226
	v_lshlrev_b32_e32 v156, 16, v227
	v_and_b32_e32 v157, 0xffff0000, v227
	v_add_f32_e32 v240, v240, v150
	v_add_f32_e32 v241, v241, v151
	v_add_f32_e32 v242, v242, v152
	v_add_f32_e32 v243, v243, v153
	v_add_f32_e32 v244, v244, v154
	v_add_f32_e32 v245, v245, v155
	v_add_f32_e32 v246, v246, v156
	v_add_f32_e32 v247, v247, v157
	v_cvt_pk_bf16_f32 v158, v240, v241
	v_cvt_pk_bf16_f32 v159, v242, v243
	v_cvt_pk_bf16_f32 v160, v244, v245
	v_cvt_pk_bf16_f32 v161, v246, v247
	v_add_u32_e32 v129, 0x40000, v131
	global_store_dwordx4 v129, v[158:161], s[10:11]
	s_waitcnt vmcnt(5)
	v_lshlrev_b32_e32 v240, 16, v212
	v_and_b32_e32 v241, 0xffff0000, v212
	v_lshlrev_b32_e32 v242, 16, v213
	v_and_b32_e32 v243, 0xffff0000, v213
	v_lshlrev_b32_e32 v244, 16, v214
	v_and_b32_e32 v245, 0xffff0000, v214
	v_lshlrev_b32_e32 v246, 16, v215
	v_and_b32_e32 v247, 0xffff0000, v215
	v_mul_f32_e32 v240, v44, v240
	v_mul_f32_e32 v241, v45, v241
	v_mul_f32_e32 v242, v46, v242
	v_mul_f32_e32 v243, v47, v243
	v_mul_f32_e32 v244, v40, v244
	v_mul_f32_e32 v245, v41, v245
	v_mul_f32_e32 v246, v42, v246
	v_mul_f32_e32 v247, v43, v247
	v_lshlrev_b32_e32 v150, 16, v228
	v_and_b32_e32 v151, 0xffff0000, v228
	v_lshlrev_b32_e32 v152, 16, v229
	v_and_b32_e32 v153, 0xffff0000, v229
	v_lshlrev_b32_e32 v154, 16, v230
	v_and_b32_e32 v155, 0xffff0000, v230
	v_lshlrev_b32_e32 v156, 16, v231
	v_and_b32_e32 v157, 0xffff0000, v231
	v_add_f32_e32 v240, v240, v150
	v_add_f32_e32 v241, v241, v151
	v_add_f32_e32 v242, v242, v152
	v_add_f32_e32 v243, v243, v153
	v_add_f32_e32 v244, v244, v154
	v_add_f32_e32 v245, v245, v155
	v_add_f32_e32 v246, v246, v156
	v_add_f32_e32 v247, v247, v157
	v_cvt_pk_bf16_f32 v166, v240, v241
	v_cvt_pk_bf16_f32 v167, v242, v243
	v_cvt_pk_bf16_f32 v168, v244, v245
	v_cvt_pk_bf16_f32 v169, v246, v247
	v_add_u32_e32 v129, 0x40000, v131
	global_store_dwordx4 v129, v[166:169], s[10:11] offset:256
	s_waitcnt vmcnt(4)
	v_lshlrev_b32_e32 v240, 16, v216
	v_and_b32_e32 v241, 0xffff0000, v216
	v_lshlrev_b32_e32 v242, 16, v217
	v_and_b32_e32 v243, 0xffff0000, v217
	v_lshlrev_b32_e32 v244, 16, v218
	v_and_b32_e32 v245, 0xffff0000, v218
	v_lshlrev_b32_e32 v246, 16, v219
	v_and_b32_e32 v247, 0xffff0000, v219
	v_mul_f32_e32 v240, v52, v240
	v_mul_f32_e32 v241, v53, v241
	v_mul_f32_e32 v242, v54, v242
	v_mul_f32_e32 v243, v55, v243
	v_mul_f32_e32 v244, v48, v244
	v_mul_f32_e32 v245, v49, v245
	v_mul_f32_e32 v246, v50, v246
	v_mul_f32_e32 v247, v51, v247
	v_lshlrev_b32_e32 v150, 16, v232
	v_and_b32_e32 v151, 0xffff0000, v232
	v_lshlrev_b32_e32 v152, 16, v233
	v_and_b32_e32 v153, 0xffff0000, v233
	v_lshlrev_b32_e32 v154, 16, v234
	v_and_b32_e32 v155, 0xffff0000, v234
	v_lshlrev_b32_e32 v156, 16, v235
	v_and_b32_e32 v157, 0xffff0000, v235
	v_add_f32_e32 v240, v240, v150
	v_add_f32_e32 v241, v241, v151
	v_add_f32_e32 v242, v242, v152
	v_add_f32_e32 v243, v243, v153
	v_add_f32_e32 v244, v244, v154
	v_add_f32_e32 v245, v245, v155
	v_add_f32_e32 v246, v246, v156
	v_add_f32_e32 v247, v247, v157
	v_cvt_pk_bf16_f32 v158, v240, v241
	v_cvt_pk_bf16_f32 v159, v242, v243
	v_cvt_pk_bf16_f32 v160, v244, v245
	v_cvt_pk_bf16_f32 v161, v246, v247
	v_add_u32_e32 v129, 0x48000, v131
	global_store_dwordx4 v129, v[158:161], s[10:11]
	s_waitcnt vmcnt(3)
; DI float bf_lo(unsigned u) { return __uint_as_float(u << 16); }
; DI float bf_hi(unsigned u) { return __uint_as_float(u & 0xffff0000u); }
; #define EPI_ROWS for (int ai = 0; ai < 2; ++ai) for (int m = 0; m < 4; ++m, ({ asm volatile("" ::: "memory"); }))
; DI void store_bf8(bf16_t* p, f32x4 a, f32x4 b) { u32x4 w; w.x = pk2(a[0], a[1]); w.y = pk2(a[2], a[3]); w.z = pk2(b[0], b[1]); w.w = pk2(b[2], b[3]); *(u32x4*)p = w; }
; DI void gemm_run(const GemmDesc& d, char* lds) {
;     ...
;         case E_PROJA: case E_PROJB: {
;             const int goff = d.epi == E_PROJA ? 0 : 1024, c8 = bcol + wc * 32 + fq * 8;
; #pragma unroll
;             EPI_ROWS { const int row = rbase + ai * 128 + m * 16;
; #pragma unroll
;                 for (int bj = 0; bj < 2; ++bj) { const int c = c8 + bj * 128; const u32x4 gw = *(const u32x4*)(P->gates + (long)row * 2048 + goff + c);
;                     f32x4 g0 = {bf_lo(gw.x), bf_hi(gw.x), bf_lo(gw.y), bf_hi(gw.y)}, g1 = {bf_lo(gw.z), bf_hi(gw.z), bf_lo(gw.w), bf_hi(gw.w)};
;                     f32x4 v0 = acc[ai][bj][m][0] * g0, v1 = acc[ai][bj][m][1] * g1;
;                     bf16_t* dst = P->merged + (long)row * 1024 + c;
;                     if (d.epi == E_PROJB) { const u32x4 pw = *(const u32x4*)dst;
;                         v0 += (f32x4){bf_lo(pw.x), bf_hi(pw.x), bf_lo(pw.y), bf_hi(pw.y)}; v1 += (f32x4){bf_lo(pw.z), bf_hi(pw.z), bf_lo(pw.w), bf_hi(pw.w)}; }
;                     store_bf8(dst, v0, v1); } }
	v_lshlrev_b32_e32 v240, 16, v220
	v_and_b32_e32 v241, 0xffff0000, v220
	v_lshlrev_b32_e32 v242, 16, v221
	v_and_b32_e32 v243, 0xffff0000, v221
	v_lshlrev_b32_e32 v244, 16, v222
	v_and_b32_e32 v245, 0xffff0000, v222
	v_lshlrev_b32_e32 v246, 16, v223
	v_and_b32_e32 v247, 0xffff0000, v223
	v_mul_f32_e32 v240, v28, v240
	v_mul_f32_e32 v241, v29, v241
	v_mul_f32_e32 v242, v30, v242
	v_mul_f32_e32 v243, v31, v243
	v_mul_f32_e32 v244, v24, v244
	v_mul_f32_e32 v245, v25, v245
	v_mul_f32_e32 v246, v26, v246
	v_mul_f32_e32 v247, v27, v247
	v_lshlrev_b32_e32 v150, 16, v236
	v_and_b32_e32 v151, 0xffff0000, v236
	v_lshlrev_b32_e32 v152, 16, v237
	v_and_b32_e32 v153, 0xffff0000, v237
	v_lshlrev_b32_e32 v154, 16, v238
	v_and_b32_e32 v155, 0xffff0000, v238
	v_lshlrev_b32_e32 v156, 16, v239
	v_and_b32_e32 v157, 0xffff0000, v239
	v_add_f32_e32 v240, v240, v150
	v_add_f32_e32 v241, v241, v151
	v_add_f32_e32 v242, v242, v152
	v_add_f32_e32 v243, v243, v153
	v_add_f32_e32 v244, v244, v154
	v_add_f32_e32 v245, v245, v155
	v_add_f32_e32 v246, v246, v156
	v_add_f32_e32 v247, v247, v157
	v_cvt_pk_bf16_f32 v166, v240, v241
	v_cvt_pk_bf16_f32 v167, v242, v243
	v_cvt_pk_bf16_f32 v168, v244, v245
	v_cvt_pk_bf16_f32 v169, v246, v247
	v_add_u32_e32 v129, 0x48000, v131
	global_store_dwordx4 v129, v[166:169], s[10:11] offset:256
	v_add_u32_e32 v128, 0xa0000, v130
	global_load_dwordx4 v[208:211], v128, s[2:3]
	v_add_u32_e32 v129, 0x50000, v131
	global_load_dwordx4 v[224:227], v129, s[10:11]
	v_add_u32_e32 v128, 0xa0000, v130
	global_load_dwordx4 v[212:215], v128, s[2:3] offset:256
	v_add_u32_e32 v129, 0x50000, v131
	global_load_dwordx4 v[228:231], v129, s[10:11] offset:256
	v_add_u32_e32 v128, 0xb0000, v130
	global_load_dwordx4 v[216:219], v128, s[2:3]
	v_add_u32_e32 v129, 0x58000, v131
	global_load_dwordx4 v[232:235], v129, s[10:11]
	v_add_u32_e32 v128, 0xb0000, v130
	global_load_dwordx4 v[220:223], v128, s[2:3] offset:256
	v_add_u32_e32 v129, 0x58000, v131
	global_load_dwordx4 v[236:239], v129, s[10:11] offset:256
	s_waitcnt vmcnt(6)
	v_lshlrev_b32_e32 v240, 16, v208
	v_and_b32_e32 v241, 0xffff0000, v208
	v_lshlrev_b32_e32 v242, 16, v209
	v_and_b32_e32 v243, 0xffff0000, v209
	v_lshlrev_b32_e32 v244, 16, v210
	v_and_b32_e32 v245, 0xffff0000, v210
	v_lshlrev_b32_e32 v246, 16, v211
	v_and_b32_e32 v247, 0xffff0000, v211
	v_mul_f32_e32 v240, v36, v240
	v_mul_f32_e32 v241, v37, v241
	v_mul_f32_e32 v242, v38, v242
	v_mul_f32_e32 v243, v39, v243
	v_mul_f32_e32 v244, v32, v244
	v_mul_f32_e32 v245, v33, v245
	v_mul_f32_e32 v246, v34, v246
	v_mul_f32_e32 v247, v35, v247
	v_lshlrev_b32_e32 v150, 16, v224
	v_and_b32_e32 v151, 0xffff0000, v224
	v_lshlrev_b32_e32 v152, 16, v225
	v_and_b32_e32 v153, 0xffff0000, v225
	v_lshlrev_b32_e32 v154, 16, v226
	v_and_b32_e32 v155, 0xffff0000, v226
	v_lshlrev_b32_e32 v156, 16, v227
	v_and_b32_e32 v157, 0xffff0000, v227
	v_add_f32_e32 v240, v240, v150
	v_add_f32_e32 v241, v241, v151
	v_add_f32_e32 v242, v242, v152
	v_add_f32_e32 v243, v243, v153
	v_add_f32_e32 v244, v244, v154
	v_add_f32_e32 v245, v245, v155
	v_add_f32_e32 v246, v246, v156
	v_add_f32_e32 v247, v247, v157
	v_cvt_pk_bf16_f32 v158, v240, v241
	v_cvt_pk_bf16_f32 v159, v242, v243
	v_cvt_pk_bf16_f32 v160, v244, v245
	v_cvt_pk_bf16_f32 v161, v246, v247
	v_add_u32_e32 v129, 0x50000, v131
	global_store_dwordx4 v129, v[158:161], s[10:11]
	s_waitcnt vmcnt(5)
	v_lshlrev_b32_e32 v240, 16, v212
	v_and_b32_e32 v241, 0xffff0000, v212
	v_lshlrev_b32_e32 v242, 16, v213
	v_and_b32_e32 v243, 0xffff0000, v213
	v_lshlrev_b32_e32 v244, 16, v214
	v_and_b32_e32 v245, 0xffff0000, v214
	v_lshlrev_b32_e32 v246, 16, v215
	v_and_b32_e32 v247, 0xffff0000, v215
	v_mul_f32_e32 v240, v12, v240
	v_mul_f32_e32 v241, v13, v241
	v_mul_f32_e32 v242, v14, v242
	v_mul_f32_e32 v243, v15, v243
	v_mul_f32_e32 v244, v8, v244
	v_mul_f32_e32 v245, v9, v245
	v_mul_f32_e32 v246, v10, v246
	v_mul_f32_e32 v247, v11, v247
	v_lshlrev_b32_e32 v150, 16, v228
	v_and_b32_e32 v151, 0xffff0000, v228
	v_lshlrev_b32_e32 v152, 16, v229
	v_and_b32_e32 v153, 0xffff0000, v229
	v_lshlrev_b32_e32 v154, 16, v230
	v_and_b32_e32 v155, 0xffff0000, v230
	v_lshlrev_b32_e32 v156, 16, v231
	v_and_b32_e32 v157, 0xffff0000, v231
	v_add_f32_e32 v240, v240, v150
	v_add_f32_e32 v241, v241, v151
	v_add_f32_e32 v242, v242, v152
	v_add_f32_e32 v243, v243, v153
	v_add_f32_e32 v244, v244, v154
	v_add_f32_e32 v245, v245, v155
	v_add_f32_e32 v246, v246, v156
	v_add_f32_e32 v247, v247, v157
	v_cvt_pk_bf16_f32 v166, v240, v241
	v_cvt_pk_bf16_f32 v167, v242, v243
	v_cvt_pk_bf16_f32 v168, v244, v245
	v_cvt_pk_bf16_f32 v169, v246, v247
	v_add_u32_e32 v129, 0x50000, v131
	global_store_dwordx4 v129, v[166:169], s[10:11] offset:256
	s_waitcnt vmcnt(4)
	v_lshlrev_b32_e32 v240, 16, v216
	v_and_b32_e32 v241, 0xffff0000, v216
	v_lshlrev_b32_e32 v242, 16, v217
	v_and_b32_e32 v243, 0xffff0000, v217
	v_lshlrev_b32_e32 v244, 16, v218
	v_and_b32_e32 v245, 0xffff0000, v218
	v_lshlrev_b32_e32 v246, 16, v219
	v_and_b32_e32 v247, 0xffff0000, v219
	v_mul_f32_e32 v240, v20, v240
	v_mul_f32_e32 v241, v21, v241
	v_mul_f32_e32 v242, v22, v242
	v_mul_f32_e32 v243, v23, v243
	v_mul_f32_e32 v244, v16, v244
	v_mul_f32_e32 v245, v17, v245
	v_mul_f32_e32 v246, v18, v246
	v_mul_f32_e32 v247, v19, v247
	v_lshlrev_b32_e32 v150, 16, v232
	v_and_b32_e32 v151, 0xffff0000, v232
	v_lshlrev_b32_e32 v152, 16, v233
	v_and_b32_e32 v153, 0xffff0000, v233
	v_lshlrev_b32_e32 v154, 16, v234
	v_and_b32_e32 v155, 0xffff0000, v234
	v_lshlrev_b32_e32 v156, 16, v235
	v_and_b32_e32 v157, 0xffff0000, v235
	v_add_f32_e32 v240, v240, v150
	v_add_f32_e32 v241, v241, v151
	v_add_f32_e32 v242, v242, v152
	v_add_f32_e32 v243, v243, v153
	v_add_f32_e32 v244, v244, v154
	v_add_f32_e32 v245, v245, v155
	v_add_f32_e32 v246, v246, v156
	v_add_f32_e32 v247, v247, v157
	v_cvt_pk_bf16_f32 v158, v240, v241
	v_cvt_pk_bf16_f32 v159, v242, v243
	v_cvt_pk_bf16_f32 v160, v244, v245
	v_cvt_pk_bf16_f32 v161, v246, v247
	v_add_u32_e32 v129, 0x58000, v131
	global_store_dwordx4 v129, v[158:161], s[10:11]
	s_waitcnt vmcnt(3)
; DI float bf_lo(unsigned u) { return __uint_as_float(u << 16); }
; DI float bf_hi(unsigned u) { return __uint_as_float(u & 0xffff0000u); }
; #define EPI_ROWS for (int ai = 0; ai < 2; ++ai) for (int m = 0; m < 4; ++m, ({ asm volatile("" ::: "memory"); }))
; DI void store_bf8(bf16_t* p, f32x4 a, f32x4 b) { u32x4 w; w.x = pk2(a[0], a[1]); w.y = pk2(a[2], a[3]); w.z = pk2(b[0], b[1]); w.w = pk2(b[2], b[3]); *(u32x4*)p = w; }
; DI void gemm_run(const GemmDesc& d, char* lds) {
;     ...
;         case E_PROJA: case E_PROJB: {
;             const int goff = d.epi == E_PROJA ? 0 : 1024, c8 = bcol + wc * 32 + fq * 8;
; #pragma unroll
;             EPI_ROWS { const int row = rbase + ai * 128 + m * 16;
; #pragma unroll
;                 for (int bj = 0; bj < 2; ++bj) { const int c = c8 + bj * 128; const u32x4 gw = *(const u32x4*)(P->gates + (long)row * 2048 + goff + c);
;                     f32x4 g0 = {bf_lo(gw.x), bf_hi(gw.x), bf_lo(gw.y), bf_hi(gw.y)}, g1 = {bf_lo(gw.z), bf_hi(gw.z), bf_lo(gw.w), bf_hi(gw.w)};
;                     f32x4 v0 = acc[ai][bj][m][0] * g0, v1 = acc[ai][bj][m][1] * g1;
;                     bf16_t* dst = P->merged + (long)row * 1024 + c;
;                     if (d.epi == E_PROJB) { const u32x4 pw = *(const u32x4*)dst;
;                         v0 += (f32x4){bf_lo(pw.x), bf_hi(pw.x), bf_lo(pw.y), bf_hi(pw.y)}; v1 += (f32x4){bf_lo(pw.z), bf_hi(pw.z), bf_lo(pw.w), bf_hi(pw.w)}; }
;                     store_bf8(dst, v0, v1); } }
	v_lshlrev_b32_e32 v240, 16, v220
	v_and_b32_e32 v241, 0xffff0000, v220
	v_lshlrev_b32_e32 v242, 16, v221
	v_and_b32_e32 v243, 0xffff0000, v221
	v_lshlrev_b32_e32 v244, 16, v222
	v_and_b32_e32 v245, 0xffff0000, v222
	v_lshlrev_b32_e32 v246, 16, v223
	v_and_b32_e32 v247, 0xffff0000, v223
	v_mul_f32_e32 v240, v4, v240
	v_mul_f32_e32 v241, v5, v241
	v_mul_f32_e32 v242, v6, v242
	v_mul_f32_e32 v243, v7, v243
	v_mul_f32_e32 v244, v0, v244
	v_mul_f32_e32 v245, v1, v245
	v_mul_f32_e32 v246, v2, v246
	v_mul_f32_e32 v247, v3, v247
	v_lshlrev_b32_e32 v150, 16, v236
	v_and_b32_e32 v151, 0xffff0000, v236
	v_lshlrev_b32_e32 v152, 16, v237
	v_and_b32_e32 v153, 0xffff0000, v237
	v_lshlrev_b32_e32 v154, 16, v238
	v_and_b32_e32 v155, 0xffff0000, v238
	v_lshlrev_b32_e32 v156, 16, v239
	v_and_b32_e32 v157, 0xffff0000, v239
	v_add_f32_e32 v240, v240, v150
	v_add_f32_e32 v241, v241, v151
	v_add_f32_e32 v242, v242, v152
	v_add_f32_e32 v243, v243, v153
	v_add_f32_e32 v244, v244, v154
	v_add_f32_e32 v245, v245, v155
	v_add_f32_e32 v246, v246, v156
	v_add_f32_e32 v247, v247, v157
	v_cvt_pk_bf16_f32 v166, v240, v241
	v_cvt_pk_bf16_f32 v167, v242, v243
	v_cvt_pk_bf16_f32 v168, v244, v245
	v_cvt_pk_bf16_f32 v169, v246, v247
	v_add_u32_e32 v129, 0x58000, v131
	global_store_dwordx4 v129, v[166:169], s[10:11] offset:256
	s_branch .Lproj_done
.Lproj_a:
	v_mov_b32_e32 v128, v130
	global_load_dwordx4 v[208:211], v128, s[2:3]
	v_mov_b32_e32 v128, v130
	global_load_dwordx4 v[212:215], v128, s[2:3] offset:256
	v_add_u32_e32 v128, 0x10000, v130
	global_load_dwordx4 v[216:219], v128, s[2:3]
	v_add_u32_e32 v128, 0x10000, v130
	global_load_dwordx4 v[220:223], v128, s[2:3] offset:256
	s_waitcnt vmcnt(3)
	v_lshlrev_b32_e32 v240, 16, v208
	v_and_b32_e32 v241, 0xffff0000, v208
	v_lshlrev_b32_e32 v242, 16, v209
	v_and_b32_e32 v243, 0xffff0000, v209
	v_lshlrev_b32_e32 v244, 16, v210
	v_and_b32_e32 v245, 0xffff0000, v210
	v_lshlrev_b32_e32 v246, 16, v211
	v_and_b32_e32 v247, 0xffff0000, v211
	v_mul_f32_e32 v240, v124, v240
	v_mul_f32_e32 v241, v125, v241
	v_mul_f32_e32 v242, v126, v242
	v_mul_f32_e32 v243, v127, v243
	v_mul_f32_e32 v244, v120, v244
	v_mul_f32_e32 v245, v121, v245
	v_mul_f32_e32 v246, v122, v246
	v_mul_f32_e32 v247, v123, v247
	v_cvt_pk_bf16_f32 v158, v240, v241
	v_cvt_pk_bf16_f32 v159, v242, v243
	v_cvt_pk_bf16_f32 v160, v244, v245
	v_cvt_pk_bf16_f32 v161, v246, v247
	v_mov_b32_e32 v129, v131
	global_store_dwordx4 v129, v[158:161], s[10:11]
	s_waitcnt vmcnt(3)
	v_lshlrev_b32_e32 v240, 16, v212
	v_and_b32_e32 v241, 0xffff0000, v212
	v_lshlrev_b32_e32 v242, 16, v213
	v_and_b32_e32 v243, 0xffff0000, v213
	v_lshlrev_b32_e32 v244, 16, v214
	v_and_b32_e32 v245, 0xffff0000, v214
	v_lshlrev_b32_e32 v246, 16, v215
	v_and_b32_e32 v247, 0xffff0000, v215
	v_mul_f32_e32 v240, v108, v240
	v_mul_f32_e32 v241, v109, v241
	v_mul_f32_e32 v242, v110, v242
	v_mul_f32_e32 v243, v111, v243
	v_mul_f32_e32 v244, v104, v244
	v_mul_f32_e32 v245, v105, v245
	v_mul_f32_e32 v246, v106, v246
	v_mul_f32_e32 v247, v107, v247
	v_cvt_pk_bf16_f32 v166, v240, v241
	v_cvt_pk_bf16_f32 v167, v242, v243
	v_cvt_pk_bf16_f32 v168, v244, v245
	v_cvt_pk_bf16_f32 v169, v246, v247
	v_mov_b32_e32 v129, v131
	global_store_dwordx4 v129, v[166:169], s[10:11] offset:256
	s_waitcnt vmcnt(3)
	v_lshlrev_b32_e32 v240, 16, v216
	v_and_b32_e32 v241, 0xffff0000, v216
	v_lshlrev_b32_e32 v242, 16, v217
	v_and_b32_e32 v243, 0xffff0000, v217
	v_lshlrev_b32_e32 v244, 16, v218
	v_and_b32_e32 v245, 0xffff0000, v218
	v_lshlrev_b32_e32 v246, 16, v219
	v_and_b32_e32 v247, 0xffff0000, v219
	v_mul_f32_e32 v240, v116, v240
	v_mul_f32_e32 v241, v117, v241
	v_mul_f32_e32 v242, v118, v242
	v_mul_f32_e32 v243, v119, v243
	v_mul_f32_e32 v244, v112, v244
	v_mul_f32_e32 v245, v113, v245
	v_mul_f32_e32 v246, v114, v246
	v_mul_f32_e32 v247, v115, v247
	v_cvt_pk_bf16_f32 v158, v240, v241
	v_cvt_pk_bf16_f32 v159, v242, v243
	v_cvt_pk_bf16_f32 v160, v244, v245
	v_cvt_pk_bf16_f32 v161, v246, v247
	v_add_u32_e32 v129, 0x8000, v131
	global_store_dwordx4 v129, v[158:161], s[10:11]
	s_waitcnt vmcnt(3)
	v_lshlrev_b32_e32 v240, 16, v220
	v_and_b32_e32 v241, 0xffff0000, v220
	v_lshlrev_b32_e32 v242, 16, v221
	v_and_b32_e32 v243, 0xffff0000, v221
	v_lshlrev_b32_e32 v244, 16, v222
	v_and_b32_e32 v245, 0xffff0000, v222
	v_lshlrev_b32_e32 v246, 16, v223
	v_and_b32_e32 v247, 0xffff0000, v223
	v_mul_f32_e32 v240, v92, v240
	v_mul_f32_e32 v241, v93, v241
	v_mul_f32_e32 v242, v94, v242
	v_mul_f32_e32 v243, v95, v243
	v_mul_f32_e32 v244, v88, v244
	v_mul_f32_e32 v245, v89, v245
	v_mul_f32_e32 v246, v90, v246
	v_mul_f32_e32 v247, v91, v247
	v_cvt_pk_bf16_f32 v166, v240, v241
	v_cvt_pk_bf16_f32 v167, v242, v243
	v_cvt_pk_bf16_f32 v168, v244, v245
	v_cvt_pk_bf16_f32 v169, v246, v247
	v_add_u32_e32 v129, 0x8000, v131
	global_store_dwordx4 v129, v[166:169], s[10:11] offset:256
	v_add_u32_e32 v128, 0x20000, v130
	global_load_dwordx4 v[208:211], v128, s[2:3]
	v_add_u32_e32 v128, 0x20000, v130
	global_load_dwordx4 v[212:215], v128, s[2:3] offset:256
	v_add_u32_e32 v128, 0x30000, v130
	global_load_dwordx4 v[216:219], v128, s[2:3]
	v_add_u32_e32 v128, 0x30000, v130
	global_load_dwordx4 v[220:223], v128, s[2:3] offset:256
	s_waitcnt vmcnt(3)
	v_lshlrev_b32_e32 v240, 16, v208
	v_and_b32_e32 v241, 0xffff0000, v208
	v_lshlrev_b32_e32 v242, 16, v209
	v_and_b32_e32 v243, 0xffff0000, v209
	v_lshlrev_b32_e32 v244, 16, v210
	v_and_b32_e32 v245, 0xffff0000, v210
	v_lshlrev_b32_e32 v246, 16, v211
	v_and_b32_e32 v247, 0xffff0000, v211
	v_mul_f32_e32 v240, v100, v240
	v_mul_f32_e32 v241, v101, v241
	v_mul_f32_e32 v242, v102, v242
	v_mul_f32_e32 v243, v103, v243
	v_mul_f32_e32 v244, v96, v244
	v_mul_f32_e32 v245, v97, v245
	v_mul_f32_e32 v246, v98, v246
	v_mul_f32_e32 v247, v99, v247
	v_cvt_pk_bf16_f32 v158, v240, v241
	v_cvt_pk_bf16_f32 v159, v242, v243
	v_cvt_pk_bf16_f32 v160, v244, v245
	v_cvt_pk_bf16_f32 v161, v246, v247
	v_add_u32_e32 v129, 0x10000, v131
	global_store_dwordx4 v129, v[158:161], s[10:11]
	s_waitcnt vmcnt(3)
; DI float bf_lo(unsigned u) { return __uint_as_float(u << 16); }
; DI float bf_hi(unsigned u) { return __uint_as_float(u & 0xffff0000u); }
; #define EPI_ROWS for (int ai = 0; ai < 2; ++ai) for (int m = 0; m < 4; ++m, ({ asm volatile("" ::: "memory"); }))
; DI void store_bf8(bf16_t* p, f32x4 a, f32x4 b) { u32x4 w; w.x = pk2(a[0], a[1]); w.y = pk2(a[2], a[3]); w.z = pk2(b[0], b[1]); w.w = pk2(b[2], b[3]); *(u32x4*)p = w; }
; DI void gemm_run(const GemmDesc& d, char* lds) {
;     ...
;         case E_PROJA: case E_PROJB: {
;             const int goff = d.epi == E_PROJA ? 0 : 1024, c8 = bcol + wc * 32 + fq * 8;
; #pragma unroll
;             EPI_ROWS { const int row = rbase + ai * 128 + m * 16;
; #pragma unroll
;                 for (int bj = 0; bj < 2; ++bj) { const int c = c8 + bj * 128; const u32x4 gw = *(const u32x4*)(P->gates + (long)row * 2048 + goff + c);
;                     f32x4 g0 = {bf_lo(gw.x), bf_hi(gw.x), bf_lo(gw.y), bf_hi(gw.y)}, g1 = {bf_lo(gw.z), bf_hi(gw.z), bf_lo(gw.w), bf_hi(gw.w)};
;                     f32x4 v0 = acc[ai][bj][m][0] * g0, v1 = acc[ai][bj][m][1] * g1;
;                     bf16_t* dst = P->merged + (long)row * 1024 + c;
;                     if (d.epi == E_PROJB) { const u32x4 pw = *(const u32x4*)dst;
;                         v0 += (f32x4){bf_lo(pw.x), bf_hi(pw.x), bf_lo(pw.y), bf_hi(pw.y)}; v1 += (f32x4){bf_lo(pw.z), bf_hi(pw.z), bf_lo(pw.w), bf_hi(pw.w)}; }
;                     store_bf8(dst, v0, v1); } }
	v_lshlrev_b32_e32 v240, 16, v212
	v_and_b32_e32 v241, 0xffff0000, v212
	v_lshlrev_b32_e32 v242, 16, v213
	v_and_b32_e32 v243, 0xffff0000, v213
	v_lshlrev_b32_e32 v244, 16, v214
	v_and_b32_e32 v245, 0xffff0000, v214
	v_lshlrev_b32_e32 v246, 16, v215
	v_and_b32_e32 v247, 0xffff0000, v215
	v_mul_f32_e32 v240, v76, v240
	v_mul_f32_e32 v241, v77, v241
	v_mul_f32_e32 v242, v78, v242
	v_mul_f32_e32 v243, v79, v243
	v_mul_f32_e32 v244, v72, v244
	v_mul_f32_e32 v245, v73, v245
	v_mul_f32_e32 v246, v74, v246
	v_mul_f32_e32 v247, v75, v247
	v_cvt_pk_bf16_f32 v166, v240, v241
	v_cvt_pk_bf16_f32 v167, v242, v243
	v_cvt_pk_bf16_f32 v168, v244, v245
	v_cvt_pk_bf16_f32 v169, v246, v247
	v_add_u32_e32 v129, 0x10000, v131
	global_store_dwordx4 v129, v[166:169], s[10:11] offset:256
	s_waitcnt vmcnt(3)
	v_lshlrev_b32_e32 v240, 16, v216
	v_and_b32_e32 v241, 0xffff0000, v216
	v_lshlrev_b32_e32 v242, 16, v217
	v_and_b32_e32 v243, 0xffff0000, v217
	v_lshlrev_b32_e32 v244, 16, v218
	v_and_b32_e32 v245, 0xffff0000, v218
	v_lshlrev_b32_e32 v246, 16, v219
	v_and_b32_e32 v247, 0xffff0000, v219
	v_mul_f32_e32 v240, v84, v240
	v_mul_f32_e32 v241, v85, v241
	v_mul_f32_e32 v242, v86, v242
	v_mul_f32_e32 v243, v87, v243
	v_mul_f32_e32 v244, v80, v244
	v_mul_f32_e32 v245, v81, v245
	v_mul_f32_e32 v246, v82, v246
	v_mul_f32_e32 v247, v83, v247
	v_cvt_pk_bf16_f32 v158, v240, v241
	v_cvt_pk_bf16_f32 v159, v242, v243
	v_cvt_pk_bf16_f32 v160, v244, v245
	v_cvt_pk_bf16_f32 v161, v246, v247
	v_add_u32_e32 v129, 0x18000, v131
	global_store_dwordx4 v129, v[158:161], s[10:11]
	s_waitcnt vmcnt(3)
	v_lshlrev_b32_e32 v240, 16, v220
	v_and_b32_e32 v241, 0xffff0000, v220
	v_lshlrev_b32_e32 v242, 16, v221
	v_and_b32_e32 v243, 0xffff0000, v221
	v_lshlrev_b32_e32 v244, 16, v222
	v_and_b32_e32 v245, 0xffff0000, v222
	v_lshlrev_b32_e32 v246, 16, v223
	v_and_b32_e32 v247, 0xffff0000, v223
	v_mul_f32_e32 v240, v68, v240
	v_mul_f32_e32 v241, v69, v241
	v_mul_f32_e32 v242, v70, v242
	v_mul_f32_e32 v243, v71, v243
	v_mul_f32_e32 v244, v64, v244
	v_mul_f32_e32 v245, v65, v245
	v_mul_f32_e32 v246, v66, v246
	v_mul_f32_e32 v247, v67, v247
	v_cvt_pk_bf16_f32 v166, v240, v241
	v_cvt_pk_bf16_f32 v167, v242, v243
	v_cvt_pk_bf16_f32 v168, v244, v245
	v_cvt_pk_bf16_f32 v169, v246, v247
	v_add_u32_e32 v129, 0x18000, v131
	global_store_dwordx4 v129, v[166:169], s[10:11] offset:256
	v_add_u32_e32 v128, 0x80000, v130
	global_load_dwordx4 v[208:211], v128, s[2:3]
	v_add_u32_e32 v128, 0x80000, v130
	global_load_dwordx4 v[212:215], v128, s[2:3] offset:256
	v_add_u32_e32 v128, 0x90000, v130
	global_load_dwordx4 v[216:219], v128, s[2:3]
	v_add_u32_e32 v128, 0x90000, v130
	global_load_dwordx4 v[220:223], v128, s[2:3] offset:256
	s_waitcnt vmcnt(3)
	v_lshlrev_b32_e32 v240, 16, v208
	v_and_b32_e32 v241, 0xffff0000, v208
	v_lshlrev_b32_e32 v242, 16, v209
	v_and_b32_e32 v243, 0xffff0000, v209
	v_lshlrev_b32_e32 v244, 16, v210
	v_and_b32_e32 v245, 0xffff0000, v210
	v_lshlrev_b32_e32 v246, 16, v211
	v_and_b32_e32 v247, 0xffff0000, v211
	v_mul_f32_e32 v240, v60, v240
	v_mul_f32_e32 v241, v61, v241
	v_mul_f32_e32 v242, v62, v242
	v_mul_f32_e32 v243, v63, v243
	v_mul_f32_e32 v244, v56, v244
	v_mul_f32_e32 v245, v57, v245
	v_mul_f32_e32 v246, v58, v246
	v_mul_f32_e32 v247, v59, v247
	v_cvt_pk_bf16_f32 v158, v240, v241
	v_cvt_pk_bf16_f32 v159, v242, v243
	v_cvt_pk_bf16_f32 v160, v244, v245
	v_cvt_pk_bf16_f32 v161, v246, v247
	v_add_u32_e32 v129, 0x40000, v131
	global_store_dwordx4 v129, v[158:161], s[10:11]
	s_waitcnt vmcnt(3)
	v_lshlrev_b32_e32 v240, 16, v212
	v_and_b32_e32 v241, 0xffff0000, v212
	v_lshlrev_b32_e32 v242, 16, v213
	v_and_b32_e32 v243, 0xffff0000, v213
	v_lshlrev_b32_e32 v244, 16, v214
	v_and_b32_e32 v245, 0xffff0000, v214
	v_lshlrev_b32_e32 v246, 16, v215
	v_and_b32_e32 v247, 0xffff0000, v215
	v_mul_f32_e32 v240, v44, v240
	v_mul_f32_e32 v241, v45, v241
	v_mul_f32_e32 v242, v46, v242
	v_mul_f32_e32 v243, v47, v243
	v_mul_f32_e32 v244, v40, v244
	v_mul_f32_e32 v245, v41, v245
	v_mul_f32_e32 v246, v42, v246
	v_mul_f32_e32 v247, v43, v247
	v_cvt_pk_bf16_f32 v166, v240, v241
	v_cvt_pk_bf16_f32 v167, v242, v243
	v_cvt_pk_bf16_f32 v168, v244, v245
	v_cvt_pk_bf16_f32 v169, v246, v247
	v_add_u32_e32 v129, 0x40000, v131
	global_store_dwordx4 v129, v[166:169], s[10:11] offset:256
	s_waitcnt vmcnt(3)
	v_lshlrev_b32_e32 v240, 16, v216
	v_and_b32_e32 v241, 0xffff0000, v216
	v_lshlrev_b32_e32 v242, 16, v217
	v_and_b32_e32 v243, 0xffff0000, v217
	v_lshlrev_b32_e32 v244, 16, v218
	v_and_b32_e32 v245, 0xffff0000, v218
	v_lshlrev_b32_e32 v246, 16, v219
	v_and_b32_e32 v247, 0xffff0000, v219
	v_mul_f32_e32 v240, v52, v240
	v_mul_f32_e32 v241, v53, v241
	v_mul_f32_e32 v242, v54, v242
	v_mul_f32_e32 v243, v55, v243
	v_mul_f32_e32 v244, v48, v244
	v_mul_f32_e32 v245, v49, v245
	v_mul_f32_e32 v246, v50, v246
	v_mul_f32_e32 v247, v51, v247
	v_cvt_pk_bf16_f32 v158, v240, v241
	v_cvt_pk_bf16_f32 v159, v242, v243
	v_cvt_pk_bf16_f32 v160, v244, v245
	v_cvt_pk_bf16_f32 v161, v246, v247
	v_add_u32_e32 v129, 0x48000, v131
	global_store_dwordx4 v129, v[158:161], s[10:11]
	s_waitcnt vmcnt(3)
; DI float bf_lo(unsigned u) { return __uint_as_float(u << 16); }
; DI float bf_hi(unsigned u) { return __uint_as_float(u & 0xffff0000u); }
; #define EPI_ROWS for (int ai = 0; ai < 2; ++ai) for (int m = 0; m < 4; ++m, ({ asm volatile("" ::: "memory"); }))
; DI void store_bf8(bf16_t* p, f32x4 a, f32x4 b) { u32x4 w; w.x = pk2(a[0], a[1]); w.y = pk2(a[2], a[3]); w.z = pk2(b[0], b[1]); w.w = pk2(b[2], b[3]); *(u32x4*)p = w; }
; DI void gemm_run(const GemmDesc& d, char* lds) {
;     ...
;                     const int qi = fr & 3, row4 = row - qi;
;                     bf16_t* vt; int ldv;
;                     if (row4 < MP) { vt = P->vaT_p + (long)(row4 >> 13) * 512 * TP + (row4 & (TP - 1)); ldv = TP; }
;                     else { const int r = row4 - MP, b = r / SKEYS; vt = P->vaT_s + (long)b * 512 * SKP + (r - b * SKEYS); ldv = SKP; }
;     ...
;         case E_PROJA: case E_PROJB: {
;             const int goff = d.epi == E_PROJA ? 0 : 1024, c8 = bcol + wc * 32 + fq * 8;
; #pragma unroll
;             EPI_ROWS { const int row = rbase + ai * 128 + m * 16;
; #pragma unroll
;                 for (int bj = 0; bj < 2; ++bj) { const int c = c8 + bj * 128; const u32x4 gw = *(const u32x4*)(P->gates + (long)row * 2048 + goff + c);
;                     f32x4 g0 = {bf_lo(gw.x), bf_hi(gw.x), bf_lo(gw.y), bf_hi(gw.y)}, g1 = {bf_lo(gw.z), bf_hi(gw.z), bf_lo(gw.w), bf_hi(gw.w)};
;                     f32x4 v0 = acc[ai][bj][m][0] * g0, v1 = acc[ai][bj][m][1] * g1;
;                     bf16_t* dst = P->merged + (long)row * 1024 + c;
;                     if (d.epi == E_PROJB) { const u32x4 pw = *(const u32x4*)dst;
;                         v0 += (f32x4){bf_lo(pw.x), bf_hi(pw.x), bf_lo(pw.y), bf_hi(pw.y)}; v1 += (f32x4){bf_lo(pw.z), bf_hi(pw.z), bf_lo(pw.w), bf_hi(pw.w)}; }
;                     store_bf8(dst, v0, v1); } }
	v_lshlrev_b32_e32 v240, 16, v220
	v_and_b32_e32 v241, 0xffff0000, v220
	v_lshlrev_b32_e32 v242, 16, v221
	v_and_b32_e32 v243, 0xffff0000, v221
	v_lshlrev_b32_e32 v244, 16, v222
	v_and_b32_e32 v245, 0xffff0000, v222
	v_lshlrev_b32_e32 v246, 16, v223
	v_and_b32_e32 v247, 0xffff0000, v223
	v_mul_f32_e32 v240, v28, v240
	v_mul_f32_e32 v241, v29, v241
	v_mul_f32_e32 v242, v30, v242
	v_mul_f32_e32 v243, v31, v243
	v_mul_f32_e32 v244, v24, v244
	v_mul_f32_e32 v245, v25, v245
	v_mul_f32_e32 v246, v26, v246
	v_mul_f32_e32 v247, v27, v247
	v_cvt_pk_bf16_f32 v166, v240, v241
	v_cvt_pk_bf16_f32 v167, v242, v243
	v_cvt_pk_bf16_f32 v168, v244, v245
	v_cvt_pk_bf16_f32 v169, v246, v247
	v_add_u32_e32 v129, 0x48000, v131
	global_store_dwordx4 v129, v[166:169], s[10:11] offset:256
	v_add_u32_e32 v128, 0xa0000, v130
	global_load_dwordx4 v[208:211], v128, s[2:3]
	v_add_u32_e32 v128, 0xa0000, v130
	global_load_dwordx4 v[212:215], v128, s[2:3] offset:256
	v_add_u32_e32 v128, 0xb0000, v130
	global_load_dwordx4 v[216:219], v128, s[2:3]
	v_add_u32_e32 v128, 0xb0000, v130
	global_load_dwordx4 v[220:223], v128, s[2:3] offset:256
	s_waitcnt vmcnt(3)
	v_lshlrev_b32_e32 v240, 16, v208
	v_and_b32_e32 v241, 0xffff0000, v208
	v_lshlrev_b32_e32 v242, 16, v209
	v_and_b32_e32 v243, 0xffff0000, v209
	v_lshlrev_b32_e32 v244, 16, v210
	v_and_b32_e32 v245, 0xffff0000, v210
	v_lshlrev_b32_e32 v246, 16, v211
	v_and_b32_e32 v247, 0xffff0000, v211
	v_mul_f32_e32 v240, v36, v240
	v_mul_f32_e32 v241, v37, v241
	v_mul_f32_e32 v242, v38, v242
	v_mul_f32_e32 v243, v39, v243
	v_mul_f32_e32 v244, v32, v244
	v_mul_f32_e32 v245, v33, v245
	v_mul_f32_e32 v246, v34, v246
	v_mul_f32_e32 v247, v35, v247
	v_cvt_pk_bf16_f32 v158, v240, v241
	v_cvt_pk_bf16_f32 v159, v242, v243
	v_cvt_pk_bf16_f32 v160, v244, v245
	v_cvt_pk_bf16_f32 v161, v246, v247
	v_add_u32_e32 v129, 0x50000, v131
	global_store_dwordx4 v129, v[158:161], s[10:11]
	s_waitcnt vmcnt(3)
	v_lshlrev_b32_e32 v240, 16, v212
	v_and_b32_e32 v241, 0xffff0000, v212
	v_lshlrev_b32_e32 v242, 16, v213
	v_and_b32_e32 v243, 0xffff0000, v213
	v_lshlrev_b32_e32 v244, 16, v214
	v_and_b32_e32 v245, 0xffff0000, v214
	v_lshlrev_b32_e32 v246, 16, v215
	v_and_b32_e32 v247, 0xffff0000, v215
	v_mul_f32_e32 v240, v12, v240
	v_mul_f32_e32 v241, v13, v241
	v_mul_f32_e32 v242, v14, v242
	v_mul_f32_e32 v243, v15, v243
	v_mul_f32_e32 v244, v8, v244
	v_mul_f32_e32 v245, v9, v245
	v_mul_f32_e32 v246, v10, v246
	v_mul_f32_e32 v247, v11, v247
	v_cvt_pk_bf16_f32 v166, v240, v241
	v_cvt_pk_bf16_f32 v167, v242, v243
	v_cvt_pk_bf16_f32 v168, v244, v245
	v_cvt_pk_bf16_f32 v169, v246, v247
	v_add_u32_e32 v129, 0x50000, v131
	global_store_dwordx4 v129, v[166:169], s[10:11] offset:256
	s_waitcnt vmcnt(3)
	v_lshlrev_b32_e32 v240, 16, v216
	v_and_b32_e32 v241, 0xffff0000, v216
	v_lshlrev_b32_e32 v242, 16, v217
	v_and_b32_e32 v243, 0xffff0000, v217
	v_lshlrev_b32_e32 v244, 16, v218
	v_and_b32_e32 v245, 0xffff0000, v218
	v_lshlrev_b32_e32 v246, 16, v219
	v_and_b32_e32 v247, 0xffff0000, v219
	v_mul_f32_e32 v240, v20, v240
	v_mul_f32_e32 v241, v21, v241
	v_mul_f32_e32 v242, v22, v242
	v_mul_f32_e32 v243, v23, v243
	v_mul_f32_e32 v244, v16, v244
	v_mul_f32_e32 v245, v17, v245
	v_mul_f32_e32 v246, v18, v246
	v_mul_f32_e32 v247, v19, v247
	v_cvt_pk_bf16_f32 v158, v240, v241
	v_cvt_pk_bf16_f32 v159, v242, v243
	v_cvt_pk_bf16_f32 v160, v244, v245
	v_cvt_pk_bf16_f32 v161, v246, v247
	v_add_u32_e32 v129, 0x58000, v131
	global_store_dwordx4 v129, v[158:161], s[10:11]
	s_waitcnt vmcnt(3)
	v_lshlrev_b32_e32 v240, 16, v220
	v_and_b32_e32 v241, 0xffff0000, v220
	v_lshlrev_b32_e32 v242, 16, v221
	v_and_b32_e32 v243, 0xffff0000, v221
	v_lshlrev_b32_e32 v244, 16, v222
	v_and_b32_e32 v245, 0xffff0000, v222
	v_lshlrev_b32_e32 v246, 16, v223
	v_and_b32_e32 v247, 0xffff0000, v223
	v_mul_f32_e32 v240, v4, v240
	v_mul_f32_e32 v241, v5, v241
	v_mul_f32_e32 v242, v6, v242
	v_mul_f32_e32 v243, v7, v243
	v_mul_f32_e32 v244, v0, v244
	v_mul_f32_e32 v245, v1, v245
	v_mul_f32_e32 v246, v2, v246
	v_mul_f32_e32 v247, v3, v247
	v_cvt_pk_bf16_f32 v166, v240, v241
	v_cvt_pk_bf16_f32 v167, v242, v243
	v_cvt_pk_bf16_f32 v168, v244, v245
	v_cvt_pk_bf16_f32 v169, v246, v247
	v_add_u32_e32 v129, 0x58000, v131
	global_store_dwordx4 v129, v[166:169], s[10:11] offset:256
.Lproj_done:
	s_mov_b64 s[2:3], 0
.LBB0_648:
	s_and_b64 vcc, exec, s[2:3]
	s_cbranch_vccz .LBB0_778
	s_cmp_gt_u32 s23, 1
	v_lshl_add_u32 v150, v206, 3, s63
	s_cselect_b64 s[2:3], -1, 0
	v_and_b32_e32 v158, 3, v205
	s_waitcnt lgkmcnt(0)
	v_and_b32_e32 v128, 1, v205
	s_movk_i32 s12, 0xfe00
	v_cmp_eq_u32_e64 s[10:11], 0, v128
	v_cmp_gt_u32_e64 s[8:9], 2, v158
	v_add3_u32 v149, v150, v158, s12
	s_mov_b64 s[12:13], -1
	s_and_b64 vcc, exec, s[2:3]
	s_cbranch_vccz .LBB0_663
	v_sub_u32_e32 v128, v146, v158
	s_movk_i32 s12, 0x3fff
	v_cmp_lt_i32_e32 vcc, s12, v128
	s_and_saveexec_b64 s[12:13], vcc
	s_xor_b64 s[12:13], exec, s[12:13]
	s_cbranch_execz .LBB0_652
	s_load_dwordx2 s[14:15], s[58:59], 0x160
	v_add_u32_e32 v129, 0xffffc000, v128
	s_mov_b32 s24, 0xfe03f81
	v_mul_hi_u32 v130, v129, s24
	v_lshrrev_b32_e32 v140, 8, v130
	v_lshlrev_b32_e32 v147, 9, v140
	s_waitcnt lgkmcnt(0)
	v_mov_b64_e32 v[130:131], s[14:15]
	s_movk_i32 s14, 0x2080
	v_mad_u64_u32 v[130:131], s[14:15], v147, s14, v[130:131]
	s_movk_i32 s14, 0xefe0
	s_nop 0
	v_mad_i32_i24 v152, v140, s14, v129
	v_ashrrev_i32_e32 v153, 31, v152
	v_lshl_add_u64 v[152:153], v[152:153], 1, v[130:131]
